# LayerNorm fix-up passes: the 20/36 serialized split-K partial and residual loads per row issued in flight together (register-renamed), one latency instead of one per load
# speedup vs baseline: 1.0409x; 1.0409x over previous
.LBB0_1834:
	v_ashrrev_i32_e32 v9, 31, v8
	v_lshlrev_b64 v[0:1], 11, v[8:9]
	v_lshl_add_u64 v[18:19], v[14:15], 0, v[0:1]
	global_load_dwordx2 v[68:69], v[18:19], off
	v_lshlrev_b64 v[2:3], 12, v[8:9]
	v_lshl_add_u64 v[36:37], v[16:17], 0, v[2:3]
	global_load_dwordx4 v[72:75], v[36:37], off
	v_add_co_u32_e32 v30, vcc, s29, v36
	v_add_u32_e32 v8, s73, v8
	s_nop 0
	v_addc_co_u32_e32 v31, vcc, 0, v37, vcc
	global_load_dwordx4 v[76:79], v[30:31], off
	v_add_co_u32_e32 v28, vcc, s31, v36
	s_waitcnt vmcnt(2)
	v_lshlrev_b32_e32 v4, 16, v68
	v_and_b32_e32 v5, 0xffff0000, v68
	v_lshlrev_b32_e32 v6, 16, v69
	v_and_b32_e32 v7, 0xffff0000, v69
	v_addc_co_u32_e32 v29, vcc, 0, v37, vcc
	global_load_dwordx4 v[80:83], v[28:29], off
	s_waitcnt vmcnt(2)
	v_pk_fma_f32 v[6:7], v[6:7], s[94:95], v[74:75] op_sel_hi:[1,0,1]
	v_pk_fma_f32 v[4:5], v[4:5], s[94:95], v[72:73] op_sel_hi:[1,0,1]
	s_waitcnt vmcnt(1)
	v_pk_add_f32 v[6:7], v[6:7], v[78:79]
	v_pk_add_f32 v[4:5], v[4:5], v[76:77]
	s_waitcnt vmcnt(0)
	v_pk_add_f32 v[20:21], v[6:7], v[82:83]
	v_add_co_u32_e32 v6, vcc, s38, v36
	v_pk_add_f32 v[22:23], v[4:5], v[80:81]
	s_nop 0
	v_addc_co_u32_e32 v7, vcc, 0, v37, vcc
	global_load_dwordx4 v[84:87], v[6:7], off
	global_load_dwordx2 v[88:89], v[18:19], off offset:512
	global_load_dwordx4 v[92:95], v[36:37], off offset:1024
	global_load_dwordx4 v[96:99], v[30:31], off offset:1024
	global_load_dwordx4 v[100:103], v[28:29], off offset:1024
	global_load_dwordx4 v[104:107], v[6:7], off offset:1024
	global_load_dwordx2 v[108:109], v[18:19], off offset:1024
	global_load_dwordx4 v[112:115], v[36:37], off offset:2048
	global_load_dwordx4 v[116:119], v[30:31], off offset:2048
	global_load_dwordx4 v[120:123], v[28:29], off offset:2048
	global_load_dwordx4 v[124:127], v[6:7], off offset:2048
	global_load_dwordx2 v[128:129], v[18:19], off offset:1536
	global_load_dwordx4 v[132:135], v[36:37], off offset:3072
	global_load_dwordx4 v[136:139], v[30:31], off offset:3072
	global_load_dwordx4 v[140:143], v[28:29], off offset:3072
	global_load_dwordx4 v[144:147], v[6:7], off offset:3072
	s_waitcnt vmcnt(15)
	v_pk_add_f32 v[0:1], v[20:21], v[86:87]
	v_pk_add_f32 v[2:3], v[22:23], v[84:85]
	s_waitcnt vmcnt(14)
	v_lshlrev_b32_e32 v24, 16, v88
	v_and_b32_e32 v25, 0xffff0000, v88
	v_lshlrev_b32_e32 v4, 16, v89
	v_and_b32_e32 v5, 0xffff0000, v89
	s_waitcnt vmcnt(13)
	v_pk_fma_f32 v[4:5], v[4:5], s[94:95], v[94:95] op_sel_hi:[1,0,1]
	v_pk_fma_f32 v[24:25], v[24:25], s[94:95], v[92:93] op_sel_hi:[1,0,1]
	s_waitcnt vmcnt(12)
	v_pk_add_f32 v[4:5], v[4:5], v[98:99]
	v_pk_add_f32 v[24:25], v[24:25], v[96:97]
	s_waitcnt vmcnt(11)
	v_pk_add_f32 v[4:5], v[4:5], v[102:103]
	v_pk_add_f32 v[26:27], v[24:25], v[100:101]
	s_waitcnt vmcnt(10)
	v_pk_add_f32 v[20:21], v[4:5], v[106:107]
	v_pk_mov_b32 v[4:5], v[2:3], v[0:1] op_sel:[1,0]
	v_mov_b32_e32 v24, v2
	v_mov_b32_e32 v25, v1
	v_pk_add_f32 v[4:5], v[4:5], v[24:25]
	v_pk_add_f32 v[22:23], v[26:27], v[104:105]
	v_add_f32_e32 v4, v4, v5
	v_add_f32_e32 v4, 0, v4
	s_waitcnt vmcnt(9)
	v_lshlrev_b32_e32 v32, 16, v108
	v_and_b32_e32 v33, 0xffff0000, v108
	v_lshlrev_b32_e32 v34, 16, v109
	v_and_b32_e32 v35, 0xffff0000, v109
	s_waitcnt vmcnt(8)
	v_pk_fma_f32 v[34:35], v[34:35], s[94:95], v[114:115] op_sel_hi:[1,0,1]
	v_pk_fma_f32 v[32:33], v[32:33], s[94:95], v[112:113] op_sel_hi:[1,0,1]
	s_waitcnt vmcnt(7)
	v_pk_add_f32 v[34:35], v[34:35], v[118:119]
	v_pk_add_f32 v[32:33], v[32:33], v[116:117]
	s_waitcnt vmcnt(6)
	v_pk_add_f32 v[26:27], v[34:35], v[122:123]
	v_pk_add_f32 v[38:39], v[32:33], v[120:121]
	s_waitcnt vmcnt(5)
	v_pk_add_f32 v[24:25], v[26:27], v[126:127]
	v_pk_add_f32 v[26:27], v[38:39], v[124:125]
	v_pk_mov_b32 v[32:33], v[22:23], v[20:21] op_sel:[1,0]
	v_mov_b32_e32 v34, v22
	v_mov_b32_e32 v35, v21
	v_pk_add_f32 v[32:33], v[32:33], v[34:35]
	s_waitcnt vmcnt(4)
	v_lshlrev_b32_e32 v40, 16, v128
	v_and_b32_e32 v41, 0xffff0000, v128
	v_lshlrev_b32_e32 v42, 16, v129
	v_and_b32_e32 v43, 0xffff0000, v129
	v_pk_add_f32 v[34:35], v[32:33], v[32:33] op_sel:[0,1] op_sel_hi:[1,0]
	v_add_f32_e32 v32, v24, v25
	s_waitcnt vmcnt(3)
	v_pk_fma_f32 v[42:43], v[42:43], s[94:95], v[134:135] op_sel_hi:[1,0,1]
	v_pk_fma_f32 v[40:41], v[40:41], s[94:95], v[132:133] op_sel_hi:[1,0,1]
	s_waitcnt vmcnt(2)
	v_pk_add_f32 v[38:39], v[42:43], v[138:139]
	v_pk_add_f32 v[36:37], v[40:41], v[136:137]
	s_waitcnt vmcnt(1)
	v_pk_add_f32 v[30:31], v[38:39], v[142:143]
	v_pk_add_f32 v[40:41], v[36:37], v[140:141]
	v_add_f32_e32 v6, v26, v27
	s_waitcnt vmcnt(0)
	v_pk_add_f32 v[28:29], v[30:31], v[146:147]
	v_pk_add_f32 v[30:31], v[40:41], v[144:145]
	v_mov_b32_e32 v7, v28
	v_mov_b32_e32 v5, v30
	v_mov_b32_e32 v35, v31
	v_mov_b32_e32 v33, v29
	v_pk_add_f32 v[4:5], v[4:5], v[34:35]
	v_pk_add_f32 v[6:7], v[6:7], v[32:33]
	s_nop 0
	v_pk_add_f32 v[4:5], v[4:5], v[6:7]
	s_nop 0
	v_add_f32_e32 v4, v4, v5
	s_nop 1
	v_add_f32_dpp v4, v4, v4 quad_perm:[1,0,3,2] row_mask:0xf bank_mask:0xf bound_ctrl:1
	s_nop 1
	v_add_f32_dpp v4, v4, v4 quad_perm:[2,3,0,1] row_mask:0xf bank_mask:0xf bound_ctrl:1
	s_nop 1
	v_add_f32_dpp v4, v4, v4 row_half_mirror row_mask:0xf bank_mask:0xf bound_ctrl:1
	s_nop 1
	v_add_f32_dpp v4, v4, v4 row_mirror row_mask:0xf bank_mask:0xf bound_ctrl:1
	s_nop 0
	v_readlane_b32 s6, v4, 16
	v_readlane_b32 s7, v4, 48
	v_readlane_b32 s2, v4, 0
	v_readlane_b32 s3, v4, 32
	v_mov_b32_e32 v4, s6
	v_mov_b32_e32 v5, s7
	v_pk_add_f32 v[4:5], s[2:3], v[4:5]
	s_nop 0
	v_add_f32_e32 v9, v4, v5
	v_fmamk_f32 v3, v9, 0xba800000, v3
	v_fmac_f32_e32 v2, 0xba800000, v9
	v_fmamk_f32 v1, v9, 0xba800000, v1
	v_fmac_f32_e32 v0, 0xba800000, v9
	v_pk_mul_f32 v[4:5], v[0:1], v[0:1]
	v_pk_mul_f32 v[6:7], v[2:3], v[2:3]
	v_fmamk_f32 v23, v9, 0xba800000, v23
	v_pk_mov_b32 v[32:33], v[6:7], v[4:5] op_sel:[1,0]
	v_mov_b32_e32 v7, v5
	v_pk_add_f32 v[4:5], v[32:33], v[6:7]
	v_fmac_f32_e32 v22, 0xba800000, v9
	v_fmamk_f32 v21, v9, 0xba800000, v21
	v_fmac_f32_e32 v20, 0xba800000, v9
	v_pk_add_f32 v[4:5], v[4:5], v[4:5] op_sel_hi:[0,1]
	v_pk_mul_f32 v[6:7], v[20:21], v[20:21]
	v_pk_mul_f32 v[32:33], v[22:23], v[22:23]
	v_fmac_f32_e32 v26, 0xba800000, v9
	v_pk_mov_b32 v[34:35], v[32:33], v[6:7] op_sel:[1,0]
	v_mov_b32_e32 v33, v7
	v_fmamk_f32 v27, v9, 0xba800000, v27
	v_fmac_f32_e32 v24, 0xba800000, v9
	v_mul_f32_e32 v4, v26, v26
	v_pk_add_f32 v[6:7], v[34:35], v[32:33]
	v_fmamk_f32 v25, v9, 0xba800000, v25
	v_pk_fma_f32 v[32:33], v[26:27], v[26:27], v[4:5] op_sel_hi:[1,1,0]
	v_mul_f32_e32 v4, v24, v24
	v_pk_add_f32 v[6:7], v[6:7], v[6:7] op_sel_hi:[0,1]
	v_pk_fma_f32 v[34:35], v[24:25], v[24:25], v[4:5] op_sel_hi:[1,1,0]
	v_fmamk_f32 v29, v9, 0xba800000, v29
	v_fmac_f32_e32 v28, 0xba800000, v9
	v_fmamk_f32 v31, v9, 0xba800000, v31
	v_fmac_f32_e32 v30, 0xba800000, v9
	v_mul_f32_e32 v32, v30, v30
	v_mul_f32_e32 v34, v31, v31
	v_mul_f32_e32 v4, v28, v28
	v_mul_f32_e32 v6, v29, v29
	v_pk_add_f32 v[32:33], v[32:33], v[34:35]
	v_pk_add_f32 v[4:5], v[4:5], v[6:7]
	s_nop 0
	v_pk_add_f32 v[4:5], v[32:33], v[4:5]
	s_nop 0
	v_add_f32_e32 v4, v4, v5
	s_nop 1
	v_add_f32_dpp v4, v4, v4 quad_perm:[1,0,3,2] row_mask:0xf bank_mask:0xf bound_ctrl:1
	s_nop 1
	v_add_f32_dpp v4, v4, v4 quad_perm:[2,3,0,1] row_mask:0xf bank_mask:0xf bound_ctrl:1
	s_nop 1
	v_add_f32_dpp v4, v4, v4 row_half_mirror row_mask:0xf bank_mask:0xf bound_ctrl:1
	s_nop 1
	v_add_f32_dpp v4, v4, v4 row_mirror row_mask:0xf bank_mask:0xf bound_ctrl:1
	s_nop 0
	v_readlane_b32 s6, v4, 16
	v_readlane_b32 s7, v4, 48
	v_readlane_b32 s2, v4, 0
	v_readlane_b32 s3, v4, 32
	v_mov_b32_e32 v4, s6
	v_mov_b32_e32 v5, s7
	v_pk_add_f32 v[4:5], s[2:3], v[4:5]
	s_nop 0
	v_add_f32_e32 v4, v4, v5
	v_fmamk_f32 v4, v4, 0x3a800000, v213
	v_cmp_gt_f32_e32 vcc, s28, v4
	v_mul_f32_e32 v5, 0x4b800000, v4
	s_nop 0
	v_cndmask_b32_e32 v4, v4, v5, vcc
	v_rsq_f32_e32 v4, v4
	s_nop 0
	v_mul_f32_e32 v5, 0x45800000, v4
	v_cndmask_b32_e32 v32, v4, v5, vcc
	v_pk_mul_f32 v[34:35], v[2:3], v[32:33] op_sel_hi:[1,0]
	v_pk_mul_f32 v[36:37], v[0:1], v[32:33] op_sel_hi:[1,0]
	v_mov_b32_e32 v38, v146
	v_mov_b32_e32 v39, v147
	global_load_dwordx4 v[0:3], v[10:11], off
	global_load_dwordx4 v[4:7], v[12:13], off
	v_pk_mul_f32 v[22:23], v[22:23], v[32:33] op_sel_hi:[1,0]
	v_pk_mul_f32 v[20:21], v[20:21], v[32:33] op_sel_hi:[1,0]
	v_cmp_lt_i32_e32 vcc, s18, v8
	s_or_b64 s[20:21], vcc, s[20:21]
	s_waitcnt vmcnt(0)
	v_pk_fma_f32 v[2:3], v[2:3], v[36:37], v[6:7]
	v_pk_fma_f32 v[0:1], v[0:1], v[34:35], v[4:5]
	s_nop 0
	v_cvt_pk_bf16_f32 v0, v0, v1
	v_cvt_pk_bf16_f32 v1, v2, v3
	global_store_dwordx2 v[18:19], v[0:1], off
	global_load_dwordx4 v[0:3], v[10:11], off offset:1024
	s_nop 0
	global_load_dwordx4 v[4:7], v[12:13], off offset:1024
	s_waitcnt vmcnt(0)
	v_pk_fma_f32 v[2:3], v[2:3], v[20:21], v[6:7]
	v_pk_fma_f32 v[0:1], v[0:1], v[22:23], v[4:5]
	v_pk_mul_f32 v[20:21], v[26:27], v[32:33] op_sel_hi:[1,0]
	v_cvt_pk_bf16_f32 v0, v0, v1
	v_cvt_pk_bf16_f32 v1, v2, v3
	global_store_dwordx2 v[18:19], v[0:1], off offset:512
	global_load_dwordx4 v[0:3], v[10:11], off offset:2048
	s_nop 0
	global_load_dwordx4 v[4:7], v[12:13], off offset:2048
	v_pk_mul_f32 v[22:23], v[24:25], v[32:33] op_sel_hi:[1,0]
	s_waitcnt vmcnt(0)
	v_pk_fma_f32 v[0:1], v[0:1], v[20:21], v[4:5]
	v_pk_fma_f32 v[2:3], v[2:3], v[22:23], v[6:7]
	v_cvt_pk_bf16_f32 v0, v0, v1
	v_cvt_pk_bf16_f32 v1, v2, v3
	global_store_dwordx2 v[18:19], v[0:1], off offset:1024
	global_load_dwordx4 v[0:3], v[10:11], off offset:3072
	s_nop 0
	global_load_dwordx4 v[4:7], v[12:13], off offset:3072
	v_pk_mul_f32 v[20:21], v[30:31], v[32:33] op_sel_hi:[1,0]
	v_pk_mul_f32 v[22:23], v[28:29], v[32:33] op_sel_hi:[1,0]
	s_waitcnt vmcnt(0)
	v_pk_fma_f32 v[0:1], v[0:1], v[20:21], v[4:5]
	v_pk_fma_f32 v[2:3], v[2:3], v[22:23], v[6:7]
	v_cvt_pk_bf16_f32 v0, v0, v1
	v_cvt_pk_bf16_f32 v1, v2, v3
	global_store_dwordx2 v[18:19], v[0:1], off offset:1536
	s_andn2_b64 exec, exec, s[20:21]
	s_cbranch_execnz .LBB0_1834

.LBB0_2226:
	v_ashrrev_i32_e32 v9, 31, v8
	s_mov_b64 s[12:13], 0x8000
	v_lshl_add_u64 v[4:5], v[8:9], 0, s[12:13]
	v_lshlrev_b64 v[0:1], 11, v[4:5]
	v_lshl_add_u64 v[20:21], v[16:17], 0, v[0:1]
	global_load_dwordx2 v[68:69], v[20:21], off
	v_lshlrev_b64 v[2:3], 12, v[8:9]
	v_lshl_add_u64 v[34:35], v[18:19], 0, v[2:3]
	global_load_dwordx4 v[72:75], v[34:35], off
	s_mov_b32 s12, 0x200000
	v_add_co_u32_e32 v32, vcc, s12, v34
	s_mov_b32 s12, 0x400000
	s_nop 0
	v_addc_co_u32_e32 v33, vcc, 0, v35, vcc
	global_load_dwordx4 v[76:79], v[32:33], off
	v_add_co_u32_e32 v40, vcc, s12, v34
	s_mov_b32 s12, 0x600000
	s_nop 0
	v_addc_co_u32_e32 v41, vcc, 0, v35, vcc
	global_load_dwordx4 v[80:83], v[40:41], off
	v_add_co_u32_e32 v44, vcc, s12, v34
	s_mov_b32 s29, 0x800000
	s_nop 0
	v_addc_co_u32_e32 v45, vcc, 0, v35, vcc
	global_load_dwordx4 v[84:87], v[44:45], off
	v_add_co_u32_e32 v42, vcc, s29, v34
	s_mov_b32 s12, 0xa00000
	s_nop 0
	v_addc_co_u32_e32 v43, vcc, 0, v35, vcc
	global_load_dwordx4 v[88:91], v[42:43], off
	v_add_co_u32_e32 v38, vcc, s12, v34
	s_mov_b32 s12, 0xc00000
	s_nop 0
	v_addc_co_u32_e32 v39, vcc, 0, v35, vcc
	global_load_dwordx4 v[92:95], v[38:39], off
	s_waitcnt vmcnt(6)
	v_lshlrev_b32_e32 v6, 16, v68
	v_and_b32_e32 v7, 0xffff0000, v68
	v_lshlrev_b32_e32 v22, 16, v69
	v_and_b32_e32 v23, 0xffff0000, v69
	s_waitcnt vmcnt(5)
	v_pk_fma_f32 v[22:23], v[22:23], s[94:95], v[74:75] op_sel_hi:[1,0,1]
	v_pk_fma_f32 v[6:7], v[6:7], s[94:95], v[72:73] op_sel_hi:[1,0,1]
	s_waitcnt vmcnt(4)
	v_pk_add_f32 v[22:23], v[22:23], v[78:79]
	v_pk_add_f32 v[6:7], v[6:7], v[76:77]
	s_waitcnt vmcnt(3)
	v_pk_add_f32 v[22:23], v[22:23], v[82:83]
	v_pk_add_f32 v[6:7], v[6:7], v[80:81]
	s_waitcnt vmcnt(2)
	v_pk_add_f32 v[22:23], v[22:23], v[86:87]
	v_pk_add_f32 v[6:7], v[6:7], v[84:85]
	s_waitcnt vmcnt(1)
	v_pk_add_f32 v[22:23], v[22:23], v[90:91]
	v_pk_add_f32 v[6:7], v[6:7], v[88:89]
	s_waitcnt vmcnt(0)
	v_pk_add_f32 v[26:27], v[22:23], v[94:95]
	v_add_co_u32_e32 v2, vcc, s12, v34
	v_pk_add_f32 v[0:1], v[6:7], v[92:93]
	s_nop 0
	v_addc_co_u32_e32 v3, vcc, 0, v35, vcc
	global_load_dwordx4 v[96:99], v[2:3], off
	s_mov_b32 s12, 0xe00000
	s_waitcnt vmcnt(0)
	v_pk_add_f32 v[6:7], v[26:27], v[98:99]
	v_pk_add_f32 v[26:27], v[0:1], v[96:97]
	v_add_co_u32_e32 v0, vcc, s12, v34
	s_nop 1
	v_addc_co_u32_e32 v1, vcc, 0, v35, vcc
	global_load_dwordx4 v[100:103], v[0:1], off
	global_load_dwordx2 v[104:105], v[20:21], off offset:512
	global_load_dwordx4 v[108:111], v[34:35], off offset:1024
	global_load_dwordx4 v[112:115], v[32:33], off offset:1024
	global_load_dwordx4 v[116:119], v[40:41], off offset:1024
	global_load_dwordx4 v[120:123], v[44:45], off offset:1024
	global_load_dwordx4 v[124:127], v[42:43], off offset:1024
	global_load_dwordx4 v[128:131], v[38:39], off offset:1024
	global_load_dwordx4 v[132:135], v[2:3], off offset:1024
	global_load_dwordx4 v[136:139], v[0:1], off offset:1024
	global_load_dwordx2 v[140:141], v[20:21], off offset:1024
	global_load_dwordx4 v[144:147], v[34:35], off offset:2048
	global_load_dwordx4 v[148:151], v[32:33], off offset:2048
	global_load_dwordx4 v[152:155], v[40:41], off offset:2048
	global_load_dwordx4 v[156:159], v[44:45], off offset:2048
	global_load_dwordx4 v[160:163], v[42:43], off offset:2048
	global_load_dwordx4 v[68:71], v[38:39], off offset:2048
	global_load_dwordx4 v[72:75], v[2:3], off offset:2048
	global_load_dwordx4 v[76:79], v[0:1], off offset:2048
	global_load_dwordx2 v[80:81], v[20:21], off offset:1536
	global_load_dwordx4 v[84:87], v[34:35], off offset:3072
	global_load_dwordx4 v[88:91], v[32:33], off offset:3072
	global_load_dwordx4 v[92:95], v[40:41], off offset:3072
	global_load_dwordx4 v[96:99], v[44:45], off offset:3072
	s_waitcnt vmcnt(23)
	v_pk_add_f32 v[30:31], v[26:27], v[100:101]
	v_pk_add_f32 v[6:7], v[6:7], v[102:103]
	global_load_dwordx4 v[100:103], v[42:43], off offset:3072
	s_waitcnt vmcnt(23)
	v_lshlrev_b32_e32 v26, 16, v104
	v_and_b32_e32 v27, 0xffff0000, v104
	v_lshlrev_b32_e32 v28, 16, v105
	v_and_b32_e32 v29, 0xffff0000, v105
	global_load_dwordx4 v[104:107], v[38:39], off offset:3072
	s_waitcnt vmcnt(23)
	v_pk_fma_f32 v[28:29], v[28:29], s[94:95], v[110:111] op_sel_hi:[1,0,1]
	v_pk_fma_f32 v[26:27], v[26:27], s[94:95], v[108:109] op_sel_hi:[1,0,1]
	global_load_dwordx4 v[108:111], v[2:3], off offset:3072
	s_waitcnt vmcnt(23)
	v_pk_add_f32 v[28:29], v[28:29], v[114:115]
	v_pk_add_f32 v[26:27], v[26:27], v[112:113]
	global_load_dwordx4 v[112:115], v[0:1], off offset:3072
	s_waitcnt vmcnt(23)
	v_pk_add_f32 v[28:29], v[28:29], v[118:119]
	v_pk_add_f32 v[26:27], v[26:27], v[116:117]
	s_waitcnt vmcnt(22)
	v_pk_add_f32 v[28:29], v[28:29], v[122:123]
	v_pk_add_f32 v[26:27], v[26:27], v[120:121]
	s_waitcnt vmcnt(21)
	v_pk_add_f32 v[28:29], v[28:29], v[126:127]
	v_pk_add_f32 v[26:27], v[26:27], v[124:125]
	s_waitcnt vmcnt(20)
	v_pk_add_f32 v[28:29], v[28:29], v[130:131]
	v_pk_add_f32 v[26:27], v[26:27], v[128:129]
	s_waitcnt vmcnt(19)
	v_pk_add_f32 v[28:29], v[28:29], v[134:135]
	v_pk_add_f32 v[36:37], v[26:27], v[132:133]
	s_waitcnt vmcnt(18)
	v_pk_add_f32 v[22:23], v[28:29], v[138:139]
	v_pk_mov_b32 v[26:27], v[30:31], v[6:7] op_sel:[1,0]
	v_mov_b32_e32 v28, v30
	v_mov_b32_e32 v29, v7
	v_pk_add_f32 v[26:27], v[26:27], v[28:29]
	v_pk_add_f32 v[24:25], v[36:37], v[136:137]
	v_add_f32_e32 v9, v26, v27
	v_add_f32_e32 v36, 0, v9
	s_waitcnt vmcnt(17)
	v_lshlrev_b32_e32 v46, 16, v140
	v_and_b32_e32 v47, 0xffff0000, v140
	v_lshlrev_b32_e32 v48, 16, v141
	v_and_b32_e32 v49, 0xffff0000, v141
	s_waitcnt vmcnt(16)
	v_pk_fma_f32 v[48:49], v[48:49], s[94:95], v[146:147] op_sel_hi:[1,0,1]
	v_pk_fma_f32 v[46:47], v[46:47], s[94:95], v[144:145] op_sel_hi:[1,0,1]
	s_waitcnt vmcnt(15)
	v_pk_add_f32 v[48:49], v[48:49], v[150:151]
	v_pk_add_f32 v[46:47], v[46:47], v[148:149]
	s_waitcnt vmcnt(14)
	v_pk_add_f32 v[48:49], v[48:49], v[154:155]
	v_pk_add_f32 v[46:47], v[46:47], v[152:153]
	s_waitcnt vmcnt(13)
	v_pk_add_f32 v[48:49], v[48:49], v[158:159]
	v_pk_add_f32 v[46:47], v[46:47], v[156:157]
	s_waitcnt vmcnt(12)
	v_pk_add_f32 v[48:49], v[48:49], v[162:163]
	v_pk_add_f32 v[46:47], v[46:47], v[160:161]
	s_waitcnt vmcnt(11)
	v_pk_add_f32 v[48:49], v[48:49], v[70:71]
	v_pk_add_f32 v[46:47], v[46:47], v[68:69]
	s_waitcnt vmcnt(10)
	v_pk_add_f32 v[28:29], v[48:49], v[74:75]
	v_pk_add_f32 v[50:51], v[46:47], v[72:73]
	s_waitcnt vmcnt(9)
	v_pk_add_f32 v[26:27], v[28:29], v[78:79]
	v_pk_add_f32 v[28:29], v[50:51], v[76:77]
	v_pk_mov_b32 v[46:47], v[24:25], v[22:23] op_sel:[1,0]
	v_mov_b32_e32 v48, v24
	v_mov_b32_e32 v49, v23
	v_pk_add_f32 v[46:47], v[46:47], v[48:49]
	s_waitcnt vmcnt(8)
	v_lshlrev_b32_e32 v54, 16, v80
	v_and_b32_e32 v55, 0xffff0000, v80
	v_lshlrev_b32_e32 v56, 16, v81
	v_and_b32_e32 v57, 0xffff0000, v81
	v_pk_add_f32 v[48:49], v[46:47], v[46:47] op_sel:[0,1] op_sel_hi:[1,0]
	v_add_f32_e32 v46, v26, v27
	s_waitcnt vmcnt(7)
	v_pk_fma_f32 v[52:53], v[56:57], s[94:95], v[86:87] op_sel_hi:[1,0,1]
	v_pk_fma_f32 v[50:51], v[54:55], s[94:95], v[84:85] op_sel_hi:[1,0,1]
	s_waitcnt vmcnt(6)
	v_pk_add_f32 v[52:53], v[52:53], v[90:91]
	v_pk_add_f32 v[50:51], v[50:51], v[88:89]
	s_waitcnt vmcnt(5)
	v_pk_add_f32 v[40:41], v[52:53], v[94:95]
	v_pk_add_f32 v[50:51], v[50:51], v[92:93]
	s_waitcnt vmcnt(4)
	v_pk_add_f32 v[40:41], v[40:41], v[98:99]
	v_pk_add_f32 v[44:45], v[50:51], v[96:97]
	s_waitcnt vmcnt(3)
	v_pk_add_f32 v[40:41], v[40:41], v[102:103]
	v_pk_add_f32 v[42:43], v[44:45], v[100:101]
	s_waitcnt vmcnt(2)
	v_pk_add_f32 v[34:35], v[40:41], v[106:107]
	v_pk_add_f32 v[42:43], v[42:43], v[104:105]
	s_waitcnt vmcnt(1)
	v_pk_add_f32 v[32:33], v[34:35], v[110:111]
	v_pk_add_f32 v[34:35], v[42:43], v[108:109]
	s_waitcnt vmcnt(0)
	v_pk_add_f32 v[32:33], v[32:33], v[114:115]
	v_pk_add_f32 v[34:35], v[34:35], v[112:113]
	v_add_f32_e32 v0, v28, v29
	v_mov_b32_e32 v37, v34
	v_mov_b32_e32 v49, v35
	v_mov_b32_e32 v1, v32
	v_mov_b32_e32 v47, v33
	v_pk_add_f32 v[2:3], v[36:37], v[48:49]
	v_pk_add_f32 v[0:1], v[0:1], v[46:47]
	s_nop 0
	v_pk_add_f32 v[0:1], v[2:3], v[0:1]
	s_nop 0
	v_add_f32_e32 v0, v0, v1
	s_nop 1
	v_add_f32_dpp v0, v0, v0 quad_perm:[1,0,3,2] row_mask:0xf bank_mask:0xf bound_ctrl:1
	s_nop 1
	v_add_f32_dpp v0, v0, v0 quad_perm:[2,3,0,1] row_mask:0xf bank_mask:0xf bound_ctrl:1
	s_nop 1
	v_add_f32_dpp v0, v0, v0 row_half_mirror row_mask:0xf bank_mask:0xf bound_ctrl:1
	s_nop 1
	v_add_f32_dpp v0, v0, v0 row_mirror row_mask:0xf bank_mask:0xf bound_ctrl:1
	s_nop 0
	v_readlane_b32 s18, v0, 16
	v_readlane_b32 s28, v0, 48
	v_readlane_b32 s12, v0, 0
	v_readlane_b32 s13, v0, 32
	v_mov_b32_e32 v0, s18
	v_mov_b32_e32 v1, s28
	v_pk_add_f32 v[0:1], s[12:13], v[0:1]
	s_nop 0
	v_add_f32_e32 v9, v0, v1
	v_fmamk_f32 v31, v9, 0xba800000, v31
	v_fmac_f32_e32 v30, 0xba800000, v9
	v_fmamk_f32 v7, v9, 0xba800000, v7
	v_fmac_f32_e32 v6, 0xba800000, v9
	v_pk_mul_f32 v[0:1], v[6:7], v[6:7]
	v_pk_mul_f32 v[2:3], v[30:31], v[30:31]
	v_fmamk_f32 v23, v9, 0xba800000, v23
	v_pk_mov_b32 v[36:37], v[2:3], v[0:1] op_sel:[1,0]
	v_mov_b32_e32 v3, v1
	v_pk_add_f32 v[0:1], v[36:37], v[2:3]
	v_fmac_f32_e32 v22, 0xba800000, v9
	v_fmamk_f32 v25, v9, 0xba800000, v25
	v_fmac_f32_e32 v24, 0xba800000, v9
	v_pk_add_f32 v[0:1], v[0:1], v[0:1] op_sel_hi:[0,1]
	v_pk_mul_f32 v[2:3], v[22:23], v[22:23]
	v_pk_mul_f32 v[36:37], v[24:25], v[24:25]
	v_fmac_f32_e32 v28, 0xba800000, v9
	v_pk_mov_b32 v[38:39], v[36:37], v[2:3] op_sel:[1,0]
	v_mov_b32_e32 v37, v3
	v_fmac_f32_e32 v26, 0xba800000, v9
	v_fmamk_f32 v29, v9, 0xba800000, v29
	v_mul_f32_e32 v0, v28, v28
	v_pk_add_f32 v[2:3], v[38:39], v[36:37]
	v_fmamk_f32 v27, v9, 0xba800000, v27
	v_pk_fma_f32 v[36:37], v[28:29], v[28:29], v[0:1] op_sel_hi:[1,1,0]
	v_mul_f32_e32 v0, v26, v26
	v_pk_add_f32 v[2:3], v[2:3], v[2:3] op_sel_hi:[0,1]
	v_pk_fma_f32 v[38:39], v[26:27], v[26:27], v[0:1] op_sel_hi:[1,1,0]
	v_fmamk_f32 v33, v9, 0xba800000, v33
	v_fmac_f32_e32 v32, 0xba800000, v9
	v_fmamk_f32 v35, v9, 0xba800000, v35
	v_fmac_f32_e32 v34, 0xba800000, v9
	v_mul_f32_e32 v36, v34, v34
	v_mul_f32_e32 v38, v35, v35
	v_mul_f32_e32 v0, v32, v32
	v_mul_f32_e32 v2, v33, v33
	v_pk_add_f32 v[36:37], v[36:37], v[38:39]
	v_pk_add_f32 v[0:1], v[0:1], v[2:3]
	s_nop 0
	v_pk_add_f32 v[0:1], v[36:37], v[0:1]
	s_nop 0
	v_add_f32_e32 v0, v0, v1
	s_nop 1
	v_add_f32_dpp v0, v0, v0 quad_perm:[1,0,3,2] row_mask:0xf bank_mask:0xf bound_ctrl:1
	s_nop 1
	v_add_f32_dpp v0, v0, v0 quad_perm:[2,3,0,1] row_mask:0xf bank_mask:0xf bound_ctrl:1
	s_nop 1
	v_add_f32_dpp v0, v0, v0 row_half_mirror row_mask:0xf bank_mask:0xf bound_ctrl:1
	s_nop 1
	v_add_f32_dpp v0, v0, v0 row_mirror row_mask:0xf bank_mask:0xf bound_ctrl:1
	s_nop 0
	v_readlane_b32 s18, v0, 16
	v_readlane_b32 s28, v0, 48
	v_readlane_b32 s12, v0, 0
	v_readlane_b32 s13, v0, 32
	v_mov_b32_e32 v0, s18
	v_mov_b32_e32 v1, s28
	v_pk_add_f32 v[0:1], s[12:13], v[0:1]
	s_nop 0
	v_add_f32_e32 v0, v0, v1
	v_fmamk_f32 v0, v0, 0x3a800000, v213
	v_cmp_gt_f32_e32 vcc, s29, v0
	v_mul_f32_e32 v1, 0x4b800000, v0
	s_nop 0
	v_cndmask_b32_e32 v0, v0, v1, vcc
	v_rsq_f32_e32 v0, v0
	s_nop 0
	v_mul_f32_e32 v1, 0x45800000, v0
	v_cndmask_b32_e32 v38, v0, v1, vcc
	v_lshlrev_b64 v[0:1], 12, v[4:5]
	v_lshl_add_u64 v[36:37], s[16:17], 0, v[0:1]
	v_pk_mul_f32 v[40:41], v[6:7], v[38:39] op_sel_hi:[1,0]
	global_load_dwordx4 v[0:3], v[12:13], off
	global_load_dwordx4 v[4:7], v[14:15], off
	v_pk_mul_f32 v[30:31], v[30:31], v[38:39] op_sel_hi:[1,0]
	s_andn2_b64 vcc, exec, s[20:21]
	s_waitcnt vmcnt(0)
	v_pk_fma_f32 v[0:1], v[0:1], v[30:31], v[4:5]
	v_cndmask_b32_e64 v4, 0, 1, s[20:21]
	v_pk_fma_f32 v[2:3], v[2:3], v[40:41], v[6:7]
	v_cmp_ne_u32_e64 s[40:41], 1, v4
	v_lshlrev_b32_e32 v4, 2, v10
	s_cbranch_vccnz .LBB0_2237
	v_mov_b32_e32 v5, v64
	v_lshl_add_u64 v[6:7], v[36:37], 0, v[4:5]
	global_store_dwordx4 v[6:7], v[0:3], off
	s_cbranch_execnz .LBB0_2229
